# final RMSNorm done by the XCD that owns the rows, last-layer barrier XCD-local too: after the prologue no cross-XCD barrier remains
# speedup vs baseline: 1.0148x; 1.0031x over previous
.Lmy_rank_skip:
	s_or_b64 exec, exec, s[60:61]
	s_waitcnt vmcnt(0) lgkmcnt(0)
	s_barrier
	v_mov_b32_e32 v1, 0x20040
	ds_read_b32 v1, v1
	v_readfirstlane_b32 s58, v0
	s_waitcnt lgkmcnt(0)
	v_readfirstlane_b32 s59, v1
	s_lshl_b32 s59, s59, 3
	s_add_i32 s59, s59, s71
	s_cmp_eq_u32 s58, 0
	s_cselect_b32 s2, s59, s2
	s_cselect_b32 s58, 1, 0
	s_nop 0
	v_writelane_b32 v255, s58, 46
	v_writelane_b32 v255, s2, 47
	s_ashr_i32 s43, s2, 31
	s_lshr_b32 s0, s43, 29
	s_add_i32 s0, s2, s0
	s_and_b32 s1, s0, -8
	s_sub_i32 s1, s2, s1
	s_add_i32 s4, s76, 0xfffffa00
	s_cmp_lt_i32 s1, 0
	s_movk_i32 s7, 0x61
	s_cselect_b32 s5, 45, 44
	s_cselect_b32 s6, 25, 24
	s_cselect_b32 s7, s7, 0x60
	s_cmpk_gt_i32 s42, 0xc0
	s_cselect_b32 s33, s4, s76
	s_add_i32 s4, s42, 0xffffff40
	s_cmpk_gt_i32 s42, 0xc0
	s_cselect_b32 s63, s4, s42
	s_add_i32 s4, s2, 0xffffff40
	s_mov_b32 s8, s76
	s_cmpk_gt_i32 s42, 0xc0
	v_writelane_b32 v254, s8, 17
	s_cselect_b32 s13, s4, s2
	s_cmpk_lt_i32 s2, 0x200
	v_writelane_b32 v254, s9, 18
	s_cselect_b64 s[8:9], -1, 0
	v_writelane_b32 v254, s8, 19
	s_add_i32 s4, s2, 0xa0
	s_bfe_u32 s4, s4, 0x50003
	v_writelane_b32 v254, s9, 20
	s_and_b32 s8, s2, 7
	s_mul_i32 s8, s8, 20
	s_add_i32 s4, s4, s8
	s_mul_i32 s8, s4, 0xcd
	s_bfe_u32 s8, s8, 0x3000d
	s_mul_i32 s9, s8, 40
	s_mul_i32 s5, s5, s1
	s_sub_i32 s9, s4, s9
	s_ashr_i32 s4, s0, 3
	s_add_i32 s5, s5, s4
	s_mul_hi_i32 s0, s5, 0x2e8ba2e9
	s_lshr_b32 s11, s0, 31
	s_ashr_i32 s0, s0, 4
	s_add_i32 s0, s0, s11
	s_mul_i32 s11, s0, 0x58
	s_sub_i32 s5, s5, s11
	s_bfe_i32 s11, s5, 0x80000
	s_bfe_u32 s11, s11, 0x3000c
	s_add_i32 s11, s5, s11
	s_bfe_i32 s12, s11, 0x80000
	s_and_b32 s11, s11, 0xf8
	s_lshl_b32 s8, s8, 2
	s_sub_i32 s5, s5, s11
	s_and_b32 s10, s8, 28
	s_lshl_b32 s0, s0, 3
	s_sext_i32_i8 s5, s5
	s_sub_i32 s10, 16, s10
	s_sext_i32_i16 s12, s12
	s_add_i32 s0, s0, s5
	s_min_u32 s10, s10, 4
	s_ashr_i32 s11, s12, 3
	s_add_i32 s0, s0, 16
	s_ashr_i32 s51, s42, 31
	s_add_u32 s48, s38, 0x4820000
	s_addc_u32 s49, s39, 0
	s_add_u32 s50, s38, 0x3820000
	s_addc_u32 s68, s39, 0
	s_add_u32 s69, s38, 0x5820000
	s_addc_u32 s62, s39, 0
	v_writelane_b32 v254, s11, 21
	s_add_u32 s14, s40, 0x4200
	v_writelane_b32 v254, s0, 22
	s_addc_u32 s15, s41, 0
	v_writelane_b32 v254, s14, 23
	s_waitcnt lgkmcnt(0)
	v_cvt_f32_ubyte0_e32 v0, s10
	v_rcp_iflag_f32_e32 v1, v0
	v_writelane_b32 v254, s15, 24
	s_add_u32 s14, s40, 0x7400
	s_addc_u32 s15, s41, 0
	v_writelane_b32 v254, s14, 25
	v_cvt_f32_ubyte0_e32 v2, s9
	v_mul_f32_e32 v1, v2, v1
	v_writelane_b32 v254, s15, 26
	s_add_u32 s14, s40, 0x7500
	s_addc_u32 s15, s41, 0
	v_writelane_b32 v254, s14, 27
	s_add_u32 s0, s40, 0x2000
	v_trunc_f32_e32 v1, v1
	v_writelane_b32 v254, s15, 28
	v_writelane_b32 v254, s0, 29
	s_addc_u32 s0, s41, 0
	s_cmpk_lt_i32 s2, 0xc0
	v_writelane_b32 v254, s0, 30
	s_cselect_b64 s[14:15], -1, 0
	v_writelane_b32 v254, s14, 31
	s_cmp_lt_i32 s13, 0
	v_cvt_u32_f32_e32 v3, v1
	v_writelane_b32 v254, s15, 32
	s_cselect_b64 s[14:15], -1, 0
	v_writelane_b32 v254, s14, 33
	s_cmpk_lt_u32 s13, 0x6c
	v_fma_f32 v1, -v1, v0, v2
	v_writelane_b32 v254, s15, 34
	s_cselect_b64 s[14:15], -1, 0
	v_writelane_b32 v254, s14, 35
	s_add_u32 s0, s40, 0x400000
	s_mov_b32 s97, 0
	v_writelane_b32 v254, s15, 36
	v_writelane_b32 v254, s0, 37
	s_addc_u32 s0, s41, 0
	v_writelane_b32 v254, s0, 38
	s_add_u32 s0, s40, 0x300000
	v_writelane_b32 v254, s0, 39
	s_addc_u32 s0, s41, 0
	s_cmpk_lt_i32 s2, 0x300
	v_writelane_b32 v254, s0, 40
	s_cselect_b64 s[14:15], -1, 0
	v_writelane_b32 v254, s14, 41
	s_lshl_b32 s0, s13, 3
	v_mov_b32_e32 v65, 0
	v_writelane_b32 v254, s15, 42
	v_writelane_b32 v254, s0, 43
	s_add_u32 s0, s40, 0x4600000
	v_writelane_b32 v254, s0, 44
	s_addc_u32 s0, s41, 0
	v_writelane_b32 v254, s0, 45
	s_add_u32 s0, s40, 0x2600000
	v_writelane_b32 v254, s0, 46
	s_addc_u32 s0, s41, 0
	v_writelane_b32 v254, s0, 47
	s_add_u32 s0, s40, 0x1e00000
	v_writelane_b32 v254, s0, 48
	s_addc_u32 s0, s41, 0
	v_writelane_b32 v254, s0, 49
	s_add_u32 s0, s40, 0x800000
	v_writelane_b32 v254, s0, 50
	s_addc_u32 s0, s41, 0
	v_writelane_b32 v254, s0, 51
	s_add_i32 s0, s2, 0xfffffe00
	s_cmp_gt_u32 s0, 0xffffff5f
	s_mul_i32 s0, s1, s6
	s_cselect_b64 s[14:15], -1, 0
	s_add_i32 s0, s0, s4
	s_ashr_i32 s5, s0, 31
	s_lshr_b32 s5, s5, 27
	s_add_i32 s5, s0, s5
	s_ashr_i32 s6, s5, 5
	s_and_b32 s5, s5, 0xffe0
	s_sub_i32 s5, s0, s5
	s_bfe_i32 s0, s5, 0x80000
	s_bfe_u32 s0, s0, 0x3000c
	s_add_i32 s11, s5, s0
	s_mul_i32 s1, s1, s7
	s_bfe_i32 s0, s11, 0x80000
	s_and_b32 s11, s11, 0xf8
	s_add_i32 s1, s1, s4
	s_sub_i32 s5, s5, s11
	s_ashr_i32 s4, s1, 31
	v_writelane_b32 v254, s14, 52
	s_lshl_b32 s6, s6, 3
	s_sext_i32_i16 s12, s0
	s_sext_i32_i8 s5, s5
	s_lshr_b32 s4, s4, 25
	v_writelane_b32 v254, s15, 53
	s_add_i32 s14, s6, s5
	s_ashr_i32 s5, s12, 3
	s_add_i32 s4, s1, s4
	v_writelane_b32 v254, s5, 54
	s_ashr_i32 s5, s4, 7
	s_and_b32 s4, s4, 0xff80
	s_sub_i32 s1, s1, s4
	s_bfe_i32 s4, s1, 0x80000
	s_bfe_u32 s4, s4, 0x3000c
	s_add_i32 s6, s1, s4
	s_bfe_i32 s4, s6, 0x80000
	s_and_b32 s6, s6, 0xf8
	s_sub_i32 s1, s1, s6
	s_lshl_b32 s5, s5, 3
	s_sext_i32_i16 s7, s4
	s_sext_i32_i8 s1, s1
	s_add_i32 s16, s5, s1
	s_ashr_i32 s1, s7, 3
	v_writelane_b32 v254, s1, 55
	s_mov_b32 s6, s16
	s_lshr_b32 s4, s7, 3
	s_ashr_i32 s17, s16, 31
	v_writelane_b32 v254, s6, 56
	s_bfe_i64 s[4:5], s[4:5], 0x100000
	s_lshl_b64 s[4:5], s[4:5], 19
	v_writelane_b32 v254, s7, 57
	s_lshl_b64 s[6:7], s[16:17], 19
	v_writelane_b32 v254, s6, 58
	s_ashr_i32 s15, s14, 31
	s_lshr_b32 s0, s12, 3
	v_writelane_b32 v254, s7, 59
	v_writelane_b32 v254, s4, 60
	s_bfe_i64 s[0:1], s[0:1], 0x100000
	v_mov_b32_e32 v229, 0x358637bd
	v_writelane_b32 v254, s5, 61
	s_lshl_b64 s[4:5], s[14:15], 19
	v_writelane_b32 v254, s4, 62
	v_mov_b32_e32 v230, 1
	v_mov_b32_e32 v190, 0x3f4ccccd
	v_writelane_b32 v254, s5, 63
	s_lshl_b64 s[4:5], s[0:1], 19
	v_writelane_b32 v255, s4, 0
	s_lshl_b64 s[0:1], s[0:1], 21
	v_mov_b32_e32 v231, 0x1000
	v_writelane_b32 v255, s5, 1
	s_mov_b32 s4, s14
	v_writelane_b32 v255, s4, 2
	v_mov_b32_e32 v232, 0x3ecc95a3
	v_mov_b32_e32 v233, 0x3c088889
	v_writelane_b32 v255, s5, 3
	s_lshl_b64 s[4:5], s[14:15], 21
	v_writelane_b32 v255, s4, 4
	v_mov_b32_e32 v234, 0x7f800000
	v_mov_b32_e32 v235, 0x7fc00000
	v_writelane_b32 v255, s5, 5
	v_writelane_b32 v255, s0, 6
	v_readfirstlane_b32 s4, v3
	v_mov_b32_e32 v236, 0xff800000
	v_writelane_b32 v255, s1, 7
	v_cmp_ge_f32_e64 s[0:1], |v1|, v0
	s_cmp_lg_u64 s[0:1], 0
	s_addc_u32 s0, s4, 0
	s_mul_i32 s1, s0, s10
	s_sub_i32 s1, s9, s1
	s_add_i32 s1, s1, s8
	s_and_b32 s1, s1, 0xff
	s_and_b32 s4, s0, 0xff
	s_cmp_gt_u32 s4, 7
	v_writelane_b32 v255, s1, 8
	s_cselect_b64 s[0:1], -1, 0
	s_cmp_lg_u64 s[0:1], 0
	s_addc_u32 s0, s4, 0
	s_load_dwordx8 s[4:11], s[80:81], 0xd0
	v_writelane_b32 v255, s0, 9
	v_writelane_b32 v255, s13, 10
	s_lshl_b32 s0, s13, 6
	v_writelane_b32 v255, s0, 11
	s_addk_i32 s0, 0xf500
	s_lshl_b32 s79, s63, 6
	s_waitcnt lgkmcnt(0)
	s_mov_b64 s[4:5], s[8:9]
	v_writelane_b32 v255, s0, 12
	s_add_u32 s0, s4, 0x1000000
	s_addc_u32 s1, s5, 0
	v_writelane_b32 v255, s0, 13
	v_mov_b32_e32 v237, 0x3e800000
	v_bfrev_b32_e32 v238, 0.5
	v_writelane_b32 v255, s1, 14
	s_load_dwordx2 s[0:1], s[80:81], 0x68
	v_mov_b64_e32 v[192:193], 0xc0
	v_mov_b64_e32 v[194:195], 0xbf
	v_not_b32_e32 v239, 30
	s_mov_b32 s55, 0x800000
	s_waitcnt lgkmcnt(0)
	s_add_u32 s0, s0, 0xb00000
	s_addc_u32 s1, s1, 0
	v_writelane_b32 v255, s0, 15
	s_movk_i32 s92, 0x3ff
	s_movk_i32 s93, 0x1600
	v_writelane_b32 v255, s1, 16
	s_add_i32 s0, 0, 0x20020
	v_writelane_b32 v255, s0, 17
	s_add_i32 s0, 0, 0x20024
	v_writelane_b32 v255, s0, 18
	s_add_i32 s0, 0, 0x12200
	v_writelane_b32 v255, s0, 19
	s_add_i32 s0, 0, 0x15800
	v_writelane_b32 v255, s0, 20
	s_brev_b32 s0, 1
	v_writelane_b32 v255, s0, 21
	s_movk_i32 s94, 0x90
	s_movk_i32 s95, 0xf7
	v_writelane_b32 v255, s1, 22
	v_writelane_b32 v255, s2, 23
	v_writelane_b32 v255, s3, 24
	v_writelane_b32 v255, s80, 25
	s_movk_i32 s46, 0x7d0
	s_add_i32 s47, 0, 0x20000
	v_writelane_b32 v255, s81, 26
	v_writelane_b32 v255, s63, 27
	v_writelane_b32 v255, s79, 28
	s_mov_b32 s52, 0x41000000
	s_movk_i32 s54, 0xfeff
	s_mov_b32 s64, 0xc800
	s_mov_b32 s65, 0xbe800000
	s_movk_i32 s78, 0x2c00
	s_mov_b64 s[28:29], 0
	s_mov_b64 s[30:31], 0x80
	s_mov_b64 s[72:73], 0
	s_mov_b32 s74, s97
	s_and_b32 s58, s2, 7
	s_lshr_b32 s59, s2, 3
	s_mul_i32 s60, s59, 43
	s_lshr_b32 s60, s60, 8
	s_mul_i32 s61, s60, 6
	s_sub_i32 s59, s59, s61
	s_lshl_b32 s61, s58, 1
	s_add_i32 s61, s61, s59
	s_lshl_b32 s58, s58, 2
	s_add_i32 s58, s58, s59
	s_add_i32 s58, s58, 14
	s_cmp_lt_u32 s59, 2
	s_cselect_b32 s58, s61, s58
	s_mov_b32 s61, 0
	v_writelane_b32 v254, s60, 54
	v_writelane_b32 v254, s60, 55
	v_writelane_b32 v254, s58, 56
	v_writelane_b32 v254, s61, 57
	v_writelane_b32 v255, s58, 2
	v_writelane_b32 v255, s61, 3
	v_writelane_b32 v254, s61, 59
	v_writelane_b32 v254, s61, 61
	v_writelane_b32 v254, s61, 63
	v_writelane_b32 v255, s61, 1
	v_writelane_b32 v255, s61, 5
	v_writelane_b32 v255, s61, 7
	s_lshl_b32 s59, s58, 19
	v_writelane_b32 v254, s59, 58
	v_writelane_b32 v254, s59, 62
	s_lshl_b32 s59, s58, 21
	v_writelane_b32 v255, s59, 4
	s_lshl_b32 s59, s60, 19
	v_writelane_b32 v254, s59, 60
	v_writelane_b32 v255, s59, 0
	s_lshl_b32 s59, s60, 21
	v_writelane_b32 v255, s59, 6
	s_and_b32 s58, s2, 7
	s_lshr_b32 s59, s2, 3
	s_cmp_lt_u32 s59, 20
	s_cbranch_scc0 .Lmy_h_lat
	s_cmp_ge_u32 s59, 10
	s_cselect_b32 s60, 1, 0
	s_mul_i32 s61, s60, 10
	s_sub_i32 s61, s59, s61
	s_lshl_b32 s58, s58, 1
	s_add_i32 s60, s60, s58
	s_cmp_gt_u32 s61, 7
	s_addc_u32 s61, s61, 0
	s_branch .Lmy_h_done

.Lmy_e_skip:
	v_readlane_b32 s7, v255, 17
	s_waitcnt vmcnt(0) expcnt(0) lgkmcnt(0)
	s_mov_b64 s[4:5], exec
	v_mov_b32_e32 v0, s7
	v_readlane_b32 s7, v255, 18
	ds_read_b32 v2, v0
	v_mbcnt_lo_u32_b32 v1, s4, 0
	v_mov_b32_e32 v0, s7
	ds_read_b32 v0, v0
	v_mbcnt_hi_u32_b32 v1, s5, v1
	s_lshl_b32 s20, s6, 6
	v_cmp_eq_u32_e32 vcc, 0, v1
	s_and_saveexec_b64 s[6:7], vcc
	s_cbranch_execz .LBB0_2277
	s_add_i32 s96, s20, 0x500
	s_lshr_b32 s9, s20, 1
	s_add_i32 s9, s9, 0xe50
	v_readlane_b32 s8, v255, 46
	s_cmp_lg_u32 s8, 0
	s_cselect_b32 s96, s9, s96
	s_lshl_b64 s[8:9], s[96:97], 2
	v_readlane_b32 s10, v254, 10
	v_readlane_b32 s11, v254, 11
	s_add_u32 s8, s10, s8
	s_addc_u32 s9, s11, s9
	s_bcnt1_i32_b64 s4, s[4:5]
	v_mov_b32_e32 v3, s4
	global_atomic_add v3, v65, v3, s[8:9] sc0

.LBB0_2292:
	v_readlane_b32 s4, v255, 46
	s_cmp_lg_u32 s4, 0
	s_cbranch_scc0 .Lmy_gl_e
	s_waitcnt vmcnt(0)
	s_branch .Lmy_exit_e

.LBB0_2310:
	v_readlane_b32 s2, v255, 47
	s_and_b32 s12, s2, 7
	s_lshr_b32 s13, s2, 3
	s_lshl_b32 s2, s12, 9
	s_lshl_b32 s13, s13, 3
	s_add_i32 s2, s2, s13
	s_lshl_b32 s12, s12, 1
	s_add_i32 s12, s12, 14
	s_lshl_b32 s16, s12, 19
	s_mov_b32 s17, 0
	s_lshl_b32 s18, s12, 14
	s_mov_b32 s19, 0
	s_lshl_b32 s20, s12, 20
	s_mov_b32 s21, 0
	s_mov_b32 s14, 0
	v_ashrrev_i32_e32 v2, 6, v228
	s_movk_i32 s0, 0x3000
	v_add_u32_e32 v8, s2, v2
	v_cmp_gt_i32_e32 vcc, s0, v8
	v_readlane_b32 s3, v254, 14
	s_and_saveexec_b64 s[0:1], vcc
	s_movk_i32 s10, 0x100
	v_readlane_b32 s11, v254, 18
	s_cbranch_execz .LBB0_2313
	v_ashrrev_i32_e32 v3, 31, v2
	s_ashr_i32 s3, s2, 31
	v_lshl_add_u64 v[6:7], v[2:3], 0, s[2:3]
	v_lshlrev_b64 v[2:3], 11, v[6:7]
	v_and_b32_e32 v9, 63, v228
	v_lshlrev_b64 v[4:5], 6, v[6:7]
	v_lshlrev_b64 v[6:7], 12, v[6:7]
	v_lshlrev_b32_e32 v0, 4, v228
	v_and_b32_e32 v10, 3, v228
	v_lshl_or_b32 v6, v9, 4, v6
	v_and_b32_e32 v0, 0x3f0, v0
	v_mov_b32_e32 v1, 0
	s_ashr_i32 s11, s10, 31
	v_lshl_or_b32 v4, v10, 4, v4
	s_mov_b64 s[2:3], 0x600000
	v_lshl_add_u64 v[6:7], s[38:39], 0, v[6:7]
	s_mov_b64 s[4:5], 0xc00
	v_lshl_add_u64 v[0:1], s[36:37], 0, v[0:1]
	v_lshl_or_b32 v2, v9, 3, v2
	s_lshl_b64 s[0:1], s[10:11], 11
	v_lshl_add_u64 v[4:5], v[4:5], 0, s[2:3]
	s_lshl_b64 s[2:3], s[10:11], 6
	v_lshl_add_u64 v[6:7], v[6:7], 0, s[4:5]
	s_lshl_b64 s[4:5], s[10:11], 12
	s_mov_b64 s[6:7], 0
	v_mov_b32_e32 v9, 0x358637bd
	s_mov_b32 s8, 0x800000
	s_movk_i32 s9, 0x2fff
.LBB0_2312:
	v_lshl_add_u64 v[26:27], s[40:41], 0, v[4:5]
	global_load_dwordx4 v[10:13], v[0:1], off
	global_load_dwordx4 v[14:17], v[0:1], off offset:1024
	global_load_dwordx4 v[18:21], v[0:1], off offset:2048
	flat_load_dwordx4 v[22:25], v[26:27]
	v_lshl_add_u64 v[28:29], s[40:41], 0, v[2:3]
	v_add_co_u32_e32 v30, vcc, 0x6600000, v28
	v_add_u32_e32 v8, s10, v8
	s_nop 0
	v_addc_co_u32_e32 v31, vcc, 0, v29, vcc
	flat_load_dwordx2 v[32:33], v[30:31]
	flat_load_dwordx2 v[34:35], v[30:31] offset:512
	flat_load_dwordx2 v[36:37], v[30:31] offset:1024
	flat_load_dwordx2 v[38:39], v[30:31] offset:1536
	global_load_dwordx4 v[26:29], v[0:1], off offset:3072
	v_cmp_lt_i32_e32 vcc, s9, v8
	s_or_b64 s[6:7], vcc, s[6:7]
	v_lshl_add_u64 v[2:3], v[2:3], 0, s[0:1]
	v_lshl_add_u64 v[4:5], v[4:5], 0, s[2:3]
	s_waitcnt vmcnt(0) lgkmcnt(0)
	v_mov_b32_e32 v30, v23
	v_mov_b32_e32 v31, v24
	v_mov_b32_e32 v23, v25
	v_pk_add_f32 v[22:23], v[30:31], v[22:23]
	v_lshlrev_b32_e32 v24, 16, v33
	v_add_f32_e32 v42, v22, v23
	v_lshlrev_b32_e32 v22, 16, v32
	v_and_b32_e32 v23, 0xffff0000, v32
	v_add_f32_dpp v42, v42, v42 quad_perm:[1,0,3,2] row_mask:0xf bank_mask:0xf bound_ctrl:1
	v_and_b32_e32 v25, 0xffff0000, v33
	v_lshlrev_b32_e32 v30, 16, v34
	v_add_f32_dpp v42, v42, v42 quad_perm:[2,3,0,1] row_mask:0xf bank_mask:0xf bound_ctrl:1
	v_fmamk_f32 v42, v42, 0x3a800000, v9
	v_mul_f32_e32 v43, 0x4b800000, v42
	v_cmp_gt_f32_e32 vcc, s8, v42
	v_and_b32_e32 v31, 0xffff0000, v34
	v_lshlrev_b32_e32 v32, 16, v35
	v_cndmask_b32_e32 v42, v42, v43, vcc
	v_rsq_f32_e32 v42, v42
	v_and_b32_e32 v33, 0xffff0000, v35
	v_lshlrev_b32_e32 v34, 16, v36
	v_and_b32_e32 v35, 0xffff0000, v36
	v_mul_f32_e32 v43, 0x45800000, v42
	v_cndmask_b32_e32 v42, v42, v43, vcc
	v_lshlrev_b32_e32 v36, 16, v37
	v_and_b32_e32 v37, 0xffff0000, v37
	v_lshlrev_b32_e32 v40, 16, v38
	v_and_b32_e32 v41, 0xffff0000, v38
	v_lshlrev_b32_e32 v38, 16, v39
	v_and_b32_e32 v39, 0xffff0000, v39
	v_pk_mul_f32 v[22:23], v[42:43], v[22:23] op_sel_hi:[0,1]
	v_pk_mul_f32 v[24:25], v[42:43], v[24:25] op_sel_hi:[0,1]
	v_pk_mul_f32 v[30:31], v[42:43], v[30:31] op_sel_hi:[0,1]
	v_pk_mul_f32 v[32:33], v[42:43], v[32:33] op_sel_hi:[0,1]
	v_pk_mul_f32 v[34:35], v[42:43], v[34:35] op_sel_hi:[0,1]
	v_pk_mul_f32 v[36:37], v[42:43], v[36:37] op_sel_hi:[0,1]
	v_pk_mul_f32 v[40:41], v[42:43], v[40:41] op_sel_hi:[0,1]
	v_pk_mul_f32 v[38:39], v[42:43], v[38:39] op_sel_hi:[0,1]
	v_pk_mul_f32 v[12:13], v[12:13], v[24:25]
	v_pk_mul_f32 v[10:11], v[10:11], v[22:23]
	v_pk_mul_f32 v[16:17], v[16:17], v[32:33]
	v_pk_mul_f32 v[14:15], v[14:15], v[30:31]
	v_pk_mul_f32 v[20:21], v[20:21], v[36:37]
	v_pk_mul_f32 v[18:19], v[18:19], v[34:35]
	v_pk_mul_f32 v[24:25], v[28:29], v[38:39]
	v_pk_mul_f32 v[22:23], v[26:27], v[40:41]
	global_store_dwordx4 v[6:7], v[10:13], off offset:-3072
	global_store_dwordx4 v[6:7], v[14:17], off offset:-2048
	global_store_dwordx4 v[6:7], v[18:21], off offset:-1024
	global_store_dwordx4 v[6:7], v[22:25], off
	v_lshl_add_u64 v[6:7], v[6:7], 0, s[4:5]
	s_add_i32 s14, s14, 1
	s_cmp_lg_u32 s14, 2
	s_cbranch_scc1 .Lmy_fn_noj
	v_lshl_add_u64 v[2:3], v[2:3], 0, s[16:17]
	v_lshl_add_u64 v[4:5], v[4:5], 0, s[18:19]
	v_lshl_add_u64 v[6:7], v[6:7], 0, s[20:21]
.Lmy_fn_noj:
	s_cmp_lt_u32 s14, 6
	s_cbranch_scc1 .LBB0_2312
